# v47: v46 + attention tile loop issues the first four K-fragment LDS reads at the loop head, ahead of the vmcnt-gated LDS writes of tile i+1 and the tile-(i+2) loads
# baseline (speedup 1.0000x reference)
; template <int PM> DI void attn_phase(const Params& p, int l, char* smem, int* s_item, int wv, int cidx) {
;     ...
;       for (int i = 0; i < ntl; ++i) {
;         const int cur = i & 1;
;         const int vprev = vcur ^ 1, vnext = vcur ^ 1;
;         const bool more = (i + 1 < ntl);
;         if (PM != 2 && more) {
; #pragma unroll
;           for (int j = 0; j < 2; ++j) {
;             *(u32x4*)(Kb0 + (cur ^ 1) * 17408 + (trow + 32 * j) * 272 + tch * 16) = kst[j];
;             *(u32x4*)(Vb0 + vnext * 20480 + (trow + 32 * j) * 320 + tch * 16) = vst[j];
;           }
;     ...
;           const char* Kc = Kb0 + cur * 17408 + l31 * 272 + dofs_b + h * 16;
;           bf16x8 kf[8];
;           if (full_d) {
; #pragma unroll
;             for (int j = 0; j < 8; ++j) kf[j] = *(const bf16x8*)(Kc + (j >> 3) * 32 * 272 + (j & 7) * 32);
.LBB0_422:
	s_and_b32 s89, s2, 1
	s_xor_b32 s93, s95, 1
	s_add_i32 s94, s2, 1
	s_mul_i32 s0, s89, 0x4400
	v_add_u32_e32 v0, s0, v234
	ds_read_b128 v[48:51], v0
	ds_read_b128 v[10:13], v0 offset:32
	ds_read_b128 v[6:9], v0 offset:64
	ds_read_b128 v[2:5], v0 offset:96
	s_cmp_ge_i32 s94, s81
	s_cbranch_scc1 .LBB0_424
	s_xor_b32 s0, s89, 1
	s_mulk_i32 s0, 0x4400
	v_or_b32_e32 v60, s0, v196
	s_mul_i32 s0, s93, 0x5000
	v_or_b32_e32 v61, s0, v196
	v_add_u32_e32 v60, v60, v246
	v_add_u32_e32 v61, v61, v247
	s_waitcnt vmcnt(3)
	ds_write_b128 v60, v[180:183]
	s_waitcnt vmcnt(2)
	ds_write_b128 v61, v[184:187] offset:34816
	s_waitcnt vmcnt(1)
	ds_write_b128 v60, v[188:191] offset:8704
	s_waitcnt vmcnt(0)
	ds_write_b128 v61, v[192:195] offset:45056

; template <int PM> DI void attn_phase(const Params& p, int l, char* smem, int* s_item, int wv, int cidx) {
;     ...
;         if (PM != 2 && i + 2 < ntl) {
;           const int inx = i + 2;
;           const int Rn = (inx < nplain) ? Rb + 64 * inx : Rb + 256 + local_t0 + 64 * (inx - nplain);
;           const u16* nbase = p.P + (size_t)(Rn + trow) * INW + tch * 8;
; #pragma unroll
;           for (int j = 0; j < 2; ++j) {
;             kst[j] = *(const u32x4*)(nbase + (size_t)j * 32 * INW + koff);
;             vst[j] = *(const u32x4*)(nbase + (size_t)j * 32 * INW + voff);
;           }
;         }
.LBB0_429:
	v_add_u32_e32 v60, s74, v239
	v_mad_i64_i32 v[52:53], s[0:1], v60, s85, v[202:203]
	v_lshl_add_u64 v[54:55], v[52:53], 0, s[96:97]
	v_lshl_add_u64 v[56:57], v[52:53], 0, s[76:77]
	v_lshl_add_u64 v[52:53], v[52:53], 0, s[98:99]
	global_load_dwordx4 v[180:183], v[54:55], off
	global_load_dwordx4 v[184:187], v[56:57], off
	v_lshl_add_u64 v[54:55], v[52:53], 0, s[96:97]
	v_lshl_add_u64 v[52:53], v[52:53], 0, s[76:77]
	global_load_dwordx4 v[188:191], v[54:55], off
	global_load_dwordx4 v[192:195], v[52:53], off

; DI f32x16 mfma32(bf16x8 a, bf16x8 b, f32x16 c) { return __builtin_amdgcn_mfma_f32_32x32x16_bf16(a, b, c, 0, 0, 0); }
; template <int PM> DI void attn_phase(const Params& p, int l, char* smem, int* s_item, int wv, int cidx) {
;     ...
;         bool active = (PM != 1);
;         const int tpos = local_t0 + 64 * (i - nplain);
;         if (i >= nplain) {
;           if (mode == 1) active = (PM != 1) && (tpos + 63 >= tq0 - 128) && (tpos <= tq0 + 31 + 128);
;           else { const int dr = (tpos >> 6) - kr0; active = (PM != 1) && (dr >= 0 && dr < 8); }
;         }
;         f32x16 sacc[2];
;         if (active) {
; #pragma unroll
;           for (int kb = 0; kb < 2; ++kb)
; #pragma unroll
;             for (int e = 0; e < 16; ++e) sacc[kb][e] = 0.f;
;           const char* Kc = Kb0 + cur * 17408 + l31 * 272 + dofs_b + h * 16;
;           bf16x8 kf[8];
;           if (full_d) {
; #pragma unroll
;             for (int j = 0; j < 8; ++j) kf[j] = *(const bf16x8*)(Kc + (j >> 3) * 32 * 272 + (j & 7) * 32);
; #pragma unroll
;             for (int j = 0; j < 16; ++j) {
;               sacc[j >> 3] = mfma32(kf[j & 7], qf[j & 7], sacc[j >> 3]);
;               if (j + 8 < 16) kf[j & 7] = *(const bf16x8*)(Kc + ((j + 8) >> 3) * 32 * 272 + ((j + 8) & 7) * 32);
;               __builtin_amdgcn_sched_barrier(0);
;             }
.LBB0_435:
	v_cndmask_b32_e64 v60, 0, 1, s[2:3]
	v_cmp_ne_u32_e64 s[74:75], 1, v60
	s_andn2_b64 vcc, exec, s[2:3]
	s_mulk_i32 s95, 0x5000
	s_cbranch_vccnz .LBB0_441
	s_mulk_i32 s89, 0x4400
	s_and_b64 vcc, exec, s[72:73]
	s_mov_b64 s[2:3], -1
	s_cbranch_vccnz .LBB0_438
	ds_read_b128 v[32:35], v0 offset:128
	ds_read_b128 v[36:39], v0 offset:160
	ds_read_b128 v[40:43], v0 offset:192
	ds_read_b128 v[44:47], v0 offset:224
	ds_read_b128 v[52:55], v0 offset:8704
	s_waitcnt lgkmcnt(8)
	v_mfma_f32_32x32x16_bf16 v[16:31], v[48:51], v[148:151], 0
	s_waitcnt lgkmcnt(7)
	v_mfma_f32_32x32x16_bf16 v[16:31], v[10:13], v[152:155], v[16:31]
	ds_read_b128 v[56:59], v0 offset:8736
	s_waitcnt lgkmcnt(7)
	v_mfma_f32_32x32x16_bf16 v[16:31], v[6:9], v[156:159], v[16:31]
	ds_read_b128 v[60:63], v0 offset:8768
	s_waitcnt lgkmcnt(7)
	v_mfma_f32_32x32x16_bf16 v[16:31], v[2:5], v[160:163], v[16:31]
	ds_read_b128 v[64:67], v0 offset:8800
	s_waitcnt lgkmcnt(7)
	v_mfma_f32_32x32x16_bf16 v[16:31], v[32:35], v[164:167], v[16:31]
	ds_read_b128 v[68:71], v0 offset:8832
	s_waitcnt lgkmcnt(7)
	v_mfma_f32_32x32x16_bf16 v[16:31], v[36:39], v[168:171], v[16:31]
	ds_read_b128 v[72:75], v0 offset:8864
	s_waitcnt lgkmcnt(7)
	v_mfma_f32_32x32x16_bf16 v[16:31], v[40:43], v[172:175], v[16:31]
	ds_read_b128 v[76:79], v0 offset:8896
	s_waitcnt lgkmcnt(7)
	v_mfma_f32_32x32x16_bf16 v[16:31], v[44:47], v[176:179], v[16:31]
	ds_read_b128 v[144:147], v0 offset:8928
	s_waitcnt lgkmcnt(7)
	v_mfma_f32_32x32x16_bf16 v[32:47], v[52:55], v[148:151], 0
	s_waitcnt lgkmcnt(6)
	v_mfma_f32_32x32x16_bf16 v[32:47], v[56:59], v[152:155], v[32:47]
	s_waitcnt lgkmcnt(5)
	v_mfma_f32_32x32x16_bf16 v[32:47], v[60:63], v[156:159], v[32:47]
	s_waitcnt lgkmcnt(4)
	v_mfma_f32_32x32x16_bf16 v[32:47], v[64:67], v[160:163], v[32:47]
	s_waitcnt lgkmcnt(3)
	v_mfma_f32_32x32x16_bf16 v[32:47], v[68:71], v[164:167], v[32:47]
	s_waitcnt lgkmcnt(2)
	v_mfma_f32_32x32x16_bf16 v[32:47], v[72:75], v[168:171], v[32:47]
	s_waitcnt lgkmcnt(1)
	v_mfma_f32_32x32x16_bf16 v[32:47], v[76:79], v[172:175], v[32:47]
	s_waitcnt lgkmcnt(0)
	v_mfma_f32_32x32x16_bf16 v[32:47], v[144:147], v[176:179], v[32:47]
	s_mov_b64 s[2:3], 0
